# first grid barrier: the 16 per-XCC arrival counters are read with one batch of loads instead of 16 dependent round trips
# speedup vs baseline: 1.0025x; 1.0025x over previous
.LBB0_860:
	v_readlane_b32 s4, v252, 17
	v_readlane_b32 s5, v252, 18
	v_readlane_b32 s6, v252, 14
	s_nop 3
	s_waitcnt lgkmcnt(0)
	global_load_dword v0, v1, s[4:5] sc1
	global_load_dword v2, v1, s[4:5] offset:256 sc1
	global_load_dword v3, v1, s[4:5] offset:512 sc1
	global_load_dword v4, v1, s[4:5] offset:768 sc1
	global_load_dword v5, v1, s[4:5] offset:1024 sc1
	global_load_dword v6, v1, s[4:5] offset:1280 sc1
	global_load_dword v7, v1, s[4:5] offset:1536 sc1
	global_load_dword v8, v1, s[4:5] offset:1792 sc1
	global_load_dword v9, v1, s[4:5] offset:2048 sc1
	global_load_dword v10, v1, s[4:5] offset:2304 sc1
	global_load_dword v11, v1, s[4:5] offset:2560 sc1
	global_load_dword v12, v1, s[4:5] offset:2816 sc1
	global_load_dword v13, v1, s[4:5] offset:3072 sc1
	global_load_dword v14, v1, s[4:5] offset:3328 sc1
	global_load_dword v15, v1, s[4:5] offset:3584 sc1
	global_load_dword v16, v1, s[4:5] offset:3840 sc1
	s_waitcnt vmcnt(0)
	v_add_u32_e32 v17, v2, v0
	v_add_u32_e32 v17, v17, v3
	v_add_u32_e32 v17, v17, v4
	v_add_u32_e32 v17, v17, v5
	v_add_u32_e32 v17, v17, v6
	v_add_u32_e32 v17, v17, v7
	v_add_u32_e32 v17, v17, v8
	v_add_u32_e32 v17, v17, v9
	v_add_u32_e32 v17, v17, v10
	v_add_u32_e32 v17, v17, v11
	v_add_u32_e32 v17, v17, v12
	v_add_u32_e32 v17, v17, v13
	v_add_u32_e32 v17, v17, v14
	v_add_u32_e32 v17, v17, v15
	v_add_u32_e32 v17, v17, v16
	s_mov_b64 s[4:5], -1
	v_cmp_eq_u32_e32 vcc, s6, v17
	s_mov_b64 s[6:7], -1
	s_cbranch_vccnz .LBB0_859
	s_and_b32 s4, s12, 0xff
	s_cmp_eq_u32 s4, 0
	s_mov_b64 s[4:5], -1
	s_mov_b64 s[8:9], -1
	s_sleep 1
	s_cbranch_scc1 .LBB0_864
	s_and_b64 vcc, exec, s[8:9]
	s_cbranch_vccz .LBB0_859
